# final row pass: streaming (nt) hint on the f32 output stores (written once, never re-read)
# speedup vs baseline: 1.0096x; 1.0069x over previous
.Lrp4_skip:
	v_lshlrev_b32_e32 v66, 16, v42
	v_and_b32_e32 v67, 0xffff0000, v42
	v_alignbit_b32 v42, v43, v42, 16
	v_and_b32_e32 v43, 0xffff0000, v43
	v_lshlrev_b32_e32 v68, 16, v44
	v_and_b32_e32 v69, 0xffff0000, v44
	v_alignbit_b32 v44, v45, v44, 16
	v_and_b32_e32 v45, 0xffff0000, v45
	v_lshlrev_b32_e32 v70, 16, v46
	v_and_b32_e32 v71, 0xffff0000, v46
	v_alignbit_b32 v46, v47, v46, 16
	v_and_b32_e32 v47, 0xffff0000, v47
	v_and_b32_e32 v42, 0xffff0000, v42
	v_and_b32_e32 v44, 0xffff0000, v44
	v_mul_f32_e32 v74, v67, v67
	v_mul_f32_e32 v75, v43, v43
	v_mul_f32_e32 v76, v69, v69
	v_mul_f32_e32 v77, v45, v45
	v_lshlrev_b32_e32 v72, 16, v48
	v_and_b32_e32 v73, 0xffff0000, v48
	v_alignbit_b32 v48, v49, v48, 16
	v_and_b32_e32 v49, 0xffff0000, v49
	v_and_b32_e32 v46, 0xffff0000, v46
	v_mul_f32_e32 v78, v71, v71
	v_mul_f32_e32 v79, v47, v47
	v_fmac_f32_e32 v74, v66, v66
	v_fmac_f32_e32 v75, v42, v42
	v_fmac_f32_e32 v76, v68, v68
	v_fmac_f32_e32 v77, v44, v44
	v_and_b32_e32 v48, 0xffff0000, v48
	v_mul_f32_e32 v80, v73, v73
	v_mul_f32_e32 v81, v49, v49
	v_fmac_f32_e32 v78, v70, v70
	v_fmac_f32_e32 v79, v46, v46
	v_add_f32_e32 v74, v74, v75
	v_add_f32_e32 v75, v76, v77
	v_fmac_f32_e32 v80, v72, v72
	v_fmac_f32_e32 v81, v48, v48
	v_add_f32_e32 v76, v78, v79
	v_add_f32_e32 v74, v74, v75
	v_add_f32_e32 v77, v80, v81
	v_add_f32_e32 v74, v74, v76
	v_add_f32_e32 v76, v74, v77
	ds_bpermute_b32 v77, v58, v76
	v_and_b32_e32 v81, 0xffff0000, v55
	v_and_b32_e32 v83, 0xffff0000, v56
	v_and_b32_e32 v85, 0xffff0000, v57
	v_lshlrev_b32_e32 v74, 16, v50
	s_waitcnt lgkmcnt(0)
	v_add_f32_e32 v78, v76, v77
	ds_bpermute_b32 v79, v59, v78
	v_and_b32_e32 v75, 0xffff0000, v50
	v_alignbit_b32 v50, v51, v50, 16
	v_lshlrev_b32_e32 v76, 16, v52
	v_and_b32_e32 v77, 0xffff0000, v52
	s_waitcnt lgkmcnt(0)
	v_add_f32_e32 v80, v78, v79
	ds_bpermute_b32 v82, v60, v80
	v_lshlrev_b32_e32 v78, 16, v54
	v_and_b32_e32 v79, 0xffff0000, v54
	v_alignbit_b32 v54, v55, v54, 16
	v_alignbit_b32 v52, v53, v52, 16
	s_waitcnt lgkmcnt(0)
	v_add_f32_e32 v55, v80, v82
	ds_bpermute_b32 v80, v61, v55
	v_lshlrev_b32_e32 v82, 16, v56
	v_alignbit_b32 v56, v57, v56, 16
	v_and_b32_e32 v84, 0xffff0000, v56
	v_pk_mul_f32 v[42:43], v[2:3], v[42:43]
	s_waitcnt lgkmcnt(0)
	v_add_f32_e32 v55, v55, v80
	ds_bpermute_b32 v57, v62, v55
	v_and_b32_e32 v80, 0xffff0000, v54
	v_pk_mul_f32 v[44:45], v[14:15], v[44:45]
	v_and_b32_e32 v51, 0xffff0000, v51
	v_and_b32_e32 v53, 0xffff0000, v53
	s_waitcnt lgkmcnt(0)
	v_add_f32_e32 v86, v55, v57
	ds_bpermute_b32 v87, v63, v86
	v_pk_mul_f32 v[54:55], v[0:1], v[66:67]
	v_pk_mul_f32 v[66:67], v[16:17], v[70:71]
	v_pk_mul_f32 v[56:57], v[12:13], v[68:69]
	v_pk_mul_f32 v[68:69], v[28:29], v[72:73]
	s_waitcnt lgkmcnt(0)
	v_add_f32_e32 v70, v86, v87
	v_fmamk_f32 v70, v70, 0x3a800000, v64
	v_mul_f32_e32 v71, 0x4f800000, v70
	v_cmp_gt_f32_e32 vcc, s17, v70
	v_and_b32_e32 v50, 0xffff0000, v50
	v_and_b32_e32 v52, 0xffff0000, v52
	v_cndmask_b32_e32 v70, v70, v71, vcc
	v_sqrt_f32_e32 v71, v70
	v_pk_mul_f32 v[46:47], v[18:19], v[46:47]
	v_pk_mul_f32 v[48:49], v[30:31], v[48:49]
	v_add_u32_e32 v72, -1, v71
	v_add_u32_e32 v73, 1, v71
	v_fma_f32 v86, -v72, v71, v70
	v_fma_f32 v87, -v73, v71, v70
	v_cmp_ge_f32_e64 s[2:3], 0, v86
	s_nop 1
	v_cndmask_b32_e64 v71, v71, v72, s[2:3]
	v_cmp_lt_f32_e64 s[2:3], 0, v87
	s_nop 1
	v_cndmask_b32_e64 v71, v71, v73, s[2:3]
	v_mul_f32_e32 v72, 0x37800000, v71
	v_cndmask_b32_e32 v71, v71, v72, vcc
	v_cmp_class_f32_e32 vcc, v70, v65
	s_nop 1
	v_cndmask_b32_e32 v70, v71, v70, vcc
	v_div_scale_f32 v71, s[2:3], v70, v70, 0.5
	v_rcp_f32_e32 v72, v71
	v_div_scale_f32 v73, vcc, 0.5, v70, 0.5
	v_fma_f32 v86, -v71, v72, 1.0
	v_fmac_f32_e32 v72, v86, v72
	v_mul_f32_e32 v86, v73, v72
	v_fma_f32 v87, -v71, v86, v73
	v_fmac_f32_e32 v86, v87, v72
	v_fma_f32 v71, -v71, v86, v73
	v_div_fmas_f32 v71, v71, v72, v86
	v_div_fixup_f32 v70, v71, v70, 0.5
	v_pk_mul_f32 v[72:73], v[54:55], v[70:71] op_sel_hi:[1,0]
	v_pk_mul_f32 v[42:43], v[42:43], v[70:71] op_sel_hi:[1,0]
	v_pk_mul_f32 v[86:87], v[56:57], v[70:71] op_sel_hi:[1,0]
	v_pk_mul_f32 v[44:45], v[44:45], v[70:71] op_sel_hi:[1,0]
	v_pk_mul_f32 v[66:67], v[66:67], v[70:71] op_sel_hi:[1,0]
	v_pk_mul_f32 v[46:47], v[46:47], v[70:71] op_sel_hi:[1,0]
	v_pk_fma_f32 v[54:55], v[32:33], v[50:51], v[42:43] op_sel_hi:[0,1,1]
	v_pk_fma_f32 v[56:57], v[32:33], v[74:75], v[72:73] op_sel_hi:[0,1,1]
	v_pk_fma_f32 v[50:51], v[32:33], v[52:53], v[44:45] op_sel_hi:[0,1,1]
	v_pk_fma_f32 v[52:53], v[32:33], v[76:77], v[86:87] op_sel_hi:[0,1,1]
	v_pk_fma_f32 v[42:43], v[32:33], v[80:81], v[46:47] op_sel_hi:[0,1,1]
	v_pk_fma_f32 v[46:47], v[32:33], v[78:79], v[66:67] op_sel_hi:[0,1,1]
	v_mul_f32_e32 v44, v57, v57
	v_mul_f32_e32 v45, v55, v55
	v_mul_f32_e32 v66, v53, v53
	v_mul_f32_e32 v67, v51, v51
	v_pk_mul_f32 v[68:69], v[68:69], v[70:71] op_sel_hi:[1,0]
	v_mul_f32_e32 v71, v47, v47
	v_mul_f32_e32 v72, v43, v43
	v_fmac_f32_e32 v44, v56, v56
	v_fmac_f32_e32 v45, v54, v54
	v_fmac_f32_e32 v66, v52, v52
	v_fmac_f32_e32 v67, v50, v50
	v_fmac_f32_e32 v71, v46, v46
	v_fmac_f32_e32 v72, v42, v42
	v_add_f32_e32 v44, v44, v45
	v_add_f32_e32 v45, v66, v67
	v_add_f32_e32 v66, v71, v72
	v_add_f32_e32 v44, v44, v45
	v_add_f32_e32 v66, v66, v44
	v_pk_mul_f32 v[44:45], v[48:49], v[70:71] op_sel_hi:[1,0]
	v_pk_fma_f32 v[48:49], v[32:33], v[82:83], v[68:69] op_sel_hi:[0,1,1]
	v_pk_fma_f32 v[44:45], v[32:33], v[84:85], v[44:45] op_sel_hi:[0,1,1]
	v_mul_f32_e32 v32, v49, v49
	v_mul_f32_e32 v67, v45, v45
	v_fmac_f32_e32 v32, v48, v48
	v_fmac_f32_e32 v67, v44, v44
	v_add_f32_e32 v32, v32, v67
	v_add_f32_e32 v32, v32, v66
	ds_bpermute_b32 v66, v58, v32
	s_waitcnt lgkmcnt(0)
	v_add_f32_e32 v32, v32, v66
	ds_bpermute_b32 v66, v59, v32
	s_waitcnt lgkmcnt(0)
	v_add_f32_e32 v32, v32, v66
	ds_bpermute_b32 v66, v60, v32
	s_waitcnt lgkmcnt(0)
	v_add_f32_e32 v32, v32, v66
	ds_bpermute_b32 v66, v61, v32
	s_waitcnt lgkmcnt(0)
	v_add_f32_e32 v32, v32, v66
	ds_bpermute_b32 v66, v62, v32
	s_waitcnt lgkmcnt(0)
	v_add_f32_e32 v32, v32, v66
	ds_bpermute_b32 v66, v63, v32
	s_waitcnt lgkmcnt(0)
	v_add_f32_e32 v32, v32, v66
	v_fmamk_f32 v32, v32, 0x3a800000, v64
	v_mul_f32_e32 v66, 0x4f800000, v32
	v_cmp_gt_f32_e32 vcc, s17, v32
	s_nop 1
	v_cndmask_b32_e32 v32, v32, v66, vcc
	v_sqrt_f32_e32 v66, v32
	s_nop 0
	v_add_u32_e32 v67, -1, v66
	v_add_u32_e32 v68, 1, v66
	v_fma_f32 v69, -v67, v66, v32
	v_fma_f32 v70, -v68, v66, v32
	v_cmp_ge_f32_e64 s[2:3], 0, v69
	s_nop 1
	v_cndmask_b32_e64 v66, v66, v67, s[2:3]
	v_cmp_lt_f32_e64 s[2:3], 0, v70
	s_nop 1
	v_cndmask_b32_e64 v66, v66, v68, s[2:3]
	v_mul_f32_e32 v67, 0x37800000, v66
	v_cndmask_b32_e32 v66, v66, v67, vcc
	v_cmp_class_f32_e32 vcc, v32, v65
	s_nop 1
	v_cndmask_b32_e32 v66, v66, v32, vcc
	v_div_scale_f32 v32, s[2:3], v66, v66, 1.0
	v_rcp_f32_e32 v67, v32
	v_div_scale_f32 v68, vcc, 1.0, v66, 1.0
	s_and_b64 s[2:3], exec, s[4:5]
	v_fma_f32 v69, -v32, v67, 1.0
	v_fmac_f32_e32 v67, v69, v67
	v_mul_f32_e32 v69, v68, v67
	v_fma_f32 v70, -v32, v69, v68
	v_fmac_f32_e32 v69, v70, v67
	v_fma_f32 v32, -v32, v69, v68
	v_div_fmas_f32 v32, v32, v67, v69
	v_div_fixup_f32 v32, v32, v66, 1.0
	s_mov_b64 vcc, s[2:3]
	s_cbranch_vccz .LBB0_1484
	s_lshl_b64 s[2:3], s[10:11], 10
	v_pk_mul_f32 v[70:71], v[10:11], v[54:55]
	v_pk_mul_f32 v[68:69], v[8:9], v[56:57]
	v_lshl_add_u64 v[72:73], s[2:3], 2, v[38:39]
	v_pk_mul_f32 v[68:69], v[68:69], v[32:33] op_sel_hi:[1,0]
	v_pk_mul_f32 v[70:71], v[70:71], v[32:33] op_sel_hi:[1,0]
	global_store_dwordx4 v[72:73], v[68:71], off nt
	s_nop 1
	v_pk_mul_f32 v[70:71], v[6:7], v[50:51]
	v_pk_mul_f32 v[68:69], v[4:5], v[52:53]
	v_pk_mul_f32 v[70:71], v[70:71], v[32:33] op_sel_hi:[1,0]
	v_pk_mul_f32 v[68:69], v[68:69], v[32:33] op_sel_hi:[1,0]
	global_store_dwordx4 v[72:73], v[68:71], off offset:1024 nt
	s_nop 1
	v_pk_mul_f32 v[70:71], v[26:27], v[42:43]
	v_pk_mul_f32 v[68:69], v[24:25], v[46:47]
	v_pk_mul_f32 v[70:71], v[70:71], v[32:33] op_sel_hi:[1,0]
	v_pk_mul_f32 v[68:69], v[68:69], v[32:33] op_sel_hi:[1,0]
	global_store_dwordx4 v[72:73], v[68:71], off offset:2048 nt
	s_nop 1
	v_pk_mul_f32 v[70:71], v[22:23], v[44:45]
	v_pk_mul_f32 v[68:69], v[20:21], v[48:49]
	v_pk_mul_f32 v[70:71], v[70:71], v[32:33] op_sel_hi:[1,0]
	v_pk_mul_f32 v[68:69], v[68:69], v[32:33] op_sel_hi:[1,0]
	global_store_dwordx4 v[72:73], v[68:71], off offset:3072 nt
	s_cbranch_execnz .LBB0_1481
	s_branch .LBB0_1485
